# split-phase grid barrier: arrive right after FFT stage 2, wait just before the channel-DFT GEMM (the branch-projection GEMMs no longer sit behind a full barrier)
# speedup vs baseline: 1.0090x; 1.0090x over previous
; template <class Epi>
; __device__ __forceinline__ void gemm_phase(LAS unsigned char* lds, const Gemm g, const StaticOrder& S, const Epi& E, const int tid) {
;     const int wid = __builtin_amdgcn_readfirstlane(tid >> 6), lane = tid & 63, wr = wid >> 2, wc = wid & 3, fr = lane & 15, fq = lane >> 4;
;     const int K = g.K, nt = K / BK;
;     unsigned voffA[2], voffB[2];
; #pragma unroll
;     for (int i = 0; i < 2; ++i) { int R, C; stage_rc(tid * 16 + i * 8192, R, C); const int Rb = (R & ~31) + perm32(R & 31);
;         voffA[i] = (unsigned)(R * g.lda + C) * 2u; voffB[i] = (unsigned)(Rb * g.ldb + C) * 2u; }
;     const size_t kstep = (size_t)(BK * 2);
;     const size_t hstepA = (size_t)HALF * g.lda * 2, hstepB = (size_t)HALF * g.ldb * 2;
;     const size_t tstepA = 2 * hstepA, tstepB = 2 * hstepB;
;     const unsigned ldsw = (unsigned)wid * 1024u;
;     const int aoff = lds_byte(wr * 64 + fr, fq * 8), boff = lds_byte(wc * 32 + fr, fq * 8);
;     ...
;     Unit cur, nxt; int ui = 0;
;     if (!S.next(0, cur)) return;
;     f32x4 acc[2][2][4][2];
;     E.init(acc, cur, wr, wc, fr, fq);
;     bf16x8 At[4][2], B0[2][2], B1[2][2];
;     const char* cA = (const char*)g.A + (size_t)cur.pm * tstepA; const char* cB = (const char*)g.Bt + (size_t)cur.pn * tstepB;
;     PG8_STAGE(PG8_SB(0, 0), cB, voffB); PG8_STAGE(PG8_SA(0, 0), cA, voffA); PG8_STAGE(PG8_SB(0, 1), cB + hstepB, voffB); PG8_STAGE(PG8_SA(0, 1), cA + hstepA, voffA);
; __device__ __forceinline__ void xcd_barrier(const XcdBarrier& b) {
;     ...
;         __builtin_amdgcn_s_waitcnt(0);
;         unsigned nloc = b.st[0], nx = b.st[1];
;         if (nloc == 0u) { xcd_barrier_complete(bar, bx, nloc, nx); b.st[0] = nloc; b.st[1] = nx; }
;         const unsigned old = xb_add(&bar[XB_XSUB(bx)], 1u);
;         const unsigned gen = old / nloc;
;         if (old + 1u == (gen + 1u) * nloc) {
;             __builtin_amdgcn_fence(__ATOMIC_RELEASE, "agent");
;             asm volatile("s_waitcnt vmcnt(0)" ::: "memory");
;             const unsigned og = xb_add(&bar[XB_TOP], 1u);
;             const unsigned tg = og / nx;
;             if (og + 1u == (tg + 1u) * nx) xb_add(&bar[XB_TOPGEN], 1u);
;             else XB_SPIN(xb_ld(&bar[XB_TOPGEN]) == tg, bar);
;             __builtin_amdgcn_fence(__ATOMIC_ACQUIRE, "agent");
;             xb_add(&bar[XB_XGEN(bx)], 1u);
;             asm volatile("s_waitcnt vmcnt(0)" ::: "memory");
.LBB0_574:
	v_readlane_b32 s0, v255, 8
	s_waitcnt lgkmcnt(0)
	s_add_u32 s14, s12, 0x38d2a000
	v_readlane_b32 s1, v255, 9
	s_addc_u32 s15, s13, 0
	s_lshl_b64 s[6:7], s[0:1], 1
	v_readlane_b32 s0, v255, 13
	s_add_u32 s34, s12, s6
	v_mov_b32_e32 v14, v246
	v_readlane_b32 s1, v255, 14
	s_addc_u32 s35, s13, s7
	s_waitcnt vmcnt(0)
	s_barrier
	s_mov_b64 s[20:21], exec
	v_readlane_b32 s16, v253, 5
	v_readlane_b32 s17, v253, 6
	s_nop 0
	s_and_b64 s[16:17], s[20:21], s[16:17]
	s_mov_b64 exec, s[16:17]
	s_cbranch_execz .Lsb_arr_done
	s_add_i32 s98, s98, 1
	v_mov_b32_e32 v0, 0x20fa0
	ds_read_b64 v[2:3], v0
	v_readlane_b32 s16, v253, 2
	v_readlane_b32 s17, v253, 3
	v_readlane_b32 s18, v253, 4
	s_lshl_b32 s18, s18, 6
	s_add_i32 s18, s18, 0x3600
	s_add_u32 s22, s16, s18
	s_addc_u32 s23, s17, 0
	s_add_u32 s16, s16, 0x3b00
	s_addc_u32 s17, s17, 0
	v_mov_b64_e32 v[4:5], s[22:23]
	v_mov_b32_e32 v8, 1
	flat_atomic_add v6, v[4:5], v8 sc0
	s_waitcnt vmcnt(0) lgkmcnt(0)
	v_readfirstlane_b32 s18, v6
	v_readfirstlane_b32 s19, v2
	s_mul_i32 s19, s19, s98
	s_add_i32 s18, s18, 1
	s_cmp_lg_u32 s18, s19
	s_cbranch_scc1 .Lsb_arr_done
	v_mov_b64_e32 v[4:5], s[16:17]
	buffer_wbl2 sc1
	s_waitcnt vmcnt(0) lgkmcnt(0)
	flat_atomic_add v7, v[4:5], v8 sc0
	s_waitcnt vmcnt(0) lgkmcnt(0)
.Lsb_arr_done:
	s_mov_b64 exec, s[20:21]
	s_and_b64 vcc, exec, s[0:1]
	v_readfirstlane_b32 s2, v14
	s_cbranch_vccnz .LBB0_590
	v_lshlrev_b32_e32 v0, 4, v14
	v_add_u32_e32 v1, 0x2000, v0
	v_ashrrev_i32_e32 v2, 31, v1
	v_lshrrev_b32_e32 v2, 22, v2
	v_add_u32_e32 v2, v1, v2
	v_ashrrev_i32_e32 v8, 10, v2
	v_mul_i32_i24_e32 v2, 0x400, v8
	v_sub_u32_e32 v1, v1, v2
	v_lshrrev_b32_e32 v2, 4, v1
	v_bitop3_b32 v1, v2, v1, 32 bitop3:0x6c
	v_ashrrev_i32_e32 v2, 31, v1
	v_lshrrev_b32_e32 v2, 26, v2
	v_add_u32_e32 v2, v1, v2
	v_lshlrev_b32_e32 v3, 3, v8
	v_ashrrev_i32_e32 v9, 6, v2
	v_and_b32_e32 v3, -16, v3
	v_add_u32_e32 v3, v9, v3
	v_and_b32_e32 v4, 3, v9
	s_mov_b32 s10, 0x1fffe0
	v_lshrrev_b32_e32 v5, 2, v3
	v_lshlrev_b32_e32 v6, 1, v3
	v_and_b32_e32 v2, 0xc0, v2
	v_and_or_b32 v4, v3, s10, v4
	v_and_b32_e32 v5, 4, v5
	v_and_b32_e32 v6, 24, v6
	v_sub_u32_e32 v1, v1, v2
	v_or3_b32 v4, v4, v5, v6
	v_lshlrev_b32_e32 v5, 5, v8
	v_ashrrev_i16_sdwa v1, v247, sext(v1) dst_sel:DWORD dst_unused:UNUSED_PAD src0_sel:DWORD src1_sel:BYTE_0
	v_and_b32_e32 v5, 32, v5
	v_bfe_i32 v10, v1, 0, 16
	v_add_lshl_u32 v1, v5, v10, 1
	v_lshl_add_u32 v152, v4, 11, v1
	v_lshl_add_u32 v154, v3, 12, v1
	v_bfe_i32 v1, v14, 27, 1
	v_lshrrev_b32_e32 v1, 22, v1
	v_add_u32_e32 v1, v0, v1
	v_and_b32_e32 v1, 0xfffffc00, v1
	v_sub_u32_e32 v0, v0, v1
	v_lshrrev_b32_e32 v1, 4, v0
	v_bitop3_b32 v1, v1, v0, 32 bitop3:0x6c
	v_ashrrev_i32_e32 v0, 31, v0
	v_lshrrev_b32_e32 v0, 26, v0
	v_add_u32_e32 v0, v1, v0
	v_ashrrev_i32_e32 v11, 6, v0
	v_ashrrev_i32_e32 v0, 31, v14
	v_lshrrev_b32_e32 v0, 26, v0
	v_add_u32_e32 v0, v14, v0
	v_ashrrev_i32_e32 v12, 6, v0
	v_lshlrev_b32_e32 v0, 3, v12
	v_and_b32_e32 v0, -16, v0
	v_add_u32_e32 v0, v11, v0
	s_add_u32 s3, s12, 0x14d2a800
	v_and_b32_e32 v2, 3, v11
	v_lshrrev_b32_e32 v3, 2, v0
	v_lshlrev_b32_e32 v4, 1, v0
	s_addc_u32 s36, s13, 0
	v_and_or_b32 v2, v0, s10, v2
	v_and_b32_e32 v3, 4, v3
	v_and_b32_e32 v4, 24, v4
	s_add_u32 s37, s34, 0x2c00000
	v_or3_b32 v2, v2, v3, v4
	v_mul_i32_i24_e32 v4, 64, v11
	s_addc_u32 s38, s35, 0
	s_ashr_i32 s4, s2, 6
	v_sub_u32_e32 v1, v1, v4
	s_ashr_i32 s5, s2, 8
	s_lshl_b32 s39, s4, 10
	v_lshlrev_b32_e32 v3, 5, v12
	v_ashrrev_i16_sdwa v1, v247, sext(v1) dst_sel:DWORD dst_unused:UNUSED_PAD src0_sel:DWORD src1_sel:BYTE_0
	v_readlane_b32 s10, v253, 20
	v_and_b32_e32 v3, 32, v3
	v_bfe_i32 v13, v1, 0, 16
	v_readlane_b32 s11, v253, 21
	s_add_u32 s28, s37, s10
	v_add_lshl_u32 v1, v3, v13, 1
	s_addc_u32 s29, s38, s11
	s_add_i32 s40, s39, 0
	v_lshl_add_u32 v184, v2, 11, v1
	s_add_i32 m0, s40, 0x10000
	v_readlane_b32 s10, v253, 18
	global_load_lds_dwordx4 v184, s[28:29]
	s_add_i32 m0, s40, 0x12000
	v_readlane_b32 s11, v253, 19
	s_add_u32 s26, s3, s10
	v_lshl_add_u32 v156, v0, 12, v1
	global_load_lds_dwordx4 v152, s[28:29]
	s_addc_u32 s27, s36, s11
	s_mov_b32 m0, s40
	s_add_i32 s41, s40, 0x2000
	global_load_lds_dwordx4 v156, s[26:27]
	s_mov_b32 m0, s41
	s_add_u32 s10, s28, 0x40000
	global_load_lds_dwordx4 v154, s[26:27]
	s_addc_u32 s11, s29, 0
	s_add_i32 m0, s40, 0x14000
	v_mov_b32_e32 v153, v185
	global_load_lds_dwordx4 v184, s[10:11]
	s_add_i32 m0, s40, 0x16000
	v_mov_b32_e32 v157, v185
	global_load_lds_dwordx4 v152, s[10:11]
	s_add_u32 s10, s26, 0x80000
	s_addc_u32 s11, s27, 0
	s_add_i32 s42, s40, 0x4000
	s_mov_b32 m0, s42
	s_add_i32 s43, s40, 0x6000
	global_load_lds_dwordx4 v156, s[10:11]
	s_mov_b32 m0, s43
	v_mov_b32_e32 v155, v185
	global_load_lds_dwordx4 v154, s[10:11]
	v_lshl_add_u64 v[6:7], s[28:29], 0, v[184:185]
	v_lshl_add_u64 v[4:5], s[28:29], 0, v[152:153]
	v_lshl_add_u64 v[2:3], s[26:27], 0, v[156:157]
	s_cmp_lg_u32 s5, 1
	v_lshl_add_u64 v[0:1], s[26:27], 0, v[154:155]
	s_cbranch_scc1 .LBB0_577
	s_barrier

; __device__ __forceinline__ unsigned xb_ld(unsigned* p)              { return __hip_atomic_load(p, __ATOMIC_RELAXED, __HIP_MEMORY_SCOPE_AGENT); }
; __device__ __forceinline__ unsigned xb_add(unsigned* p, unsigned v) { return __hip_atomic_fetch_add(p, v, __ATOMIC_RELAXED, __HIP_MEMORY_SCOPE_AGENT); }
; #define XB_SPIN(cond, bar) do { unsigned _sp = 0; while (cond) { __builtin_amdgcn_s_sleep(1); \
;     if ((++_sp & 255u) == 0u) { if (xb_ld(&(bar)[XB_TMO])) break; if (_sp > XB_SPIN_CAP) { atomicAdd(&(bar)[XB_TMO], 1u); break; } } } } while (0)
; __device__ __forceinline__ void xcd_barrier(const XcdBarrier& b) {
;     asm volatile("s_waitcnt vmcnt(0)" ::: "memory");
;     __syncthreads();
;     if (threadIdx.x == 0) {
;         unsigned long long bar_ = (unsigned long long)b.bar; unsigned bx = b.x;
;         asm volatile("" : "+s"(bar_), "+s"(bx));
;         unsigned* bar = (unsigned*)bar_;
;         __builtin_amdgcn_s_waitcnt(0);
;         unsigned nloc = b.st[0], nx = b.st[1];
;         if (nloc == 0u) { xcd_barrier_complete(bar, bx, nloc, nx); b.st[0] = nloc; b.st[1] = nx; }
;         const unsigned old = xb_add(&bar[XB_XSUB(bx)], 1u);
;         const unsigned gen = old / nloc;
;         if (old + 1u == (gen + 1u) * nloc) {
;             __builtin_amdgcn_fence(__ATOMIC_RELEASE, "agent");
;             asm volatile("s_waitcnt vmcnt(0)" ::: "memory");
;             const unsigned og = xb_add(&bar[XB_TOP], 1u);
;             const unsigned tg = og / nx;
;             if (og + 1u == (tg + 1u) * nx) xb_add(&bar[XB_TOPGEN], 1u);
;             else XB_SPIN(xb_ld(&bar[XB_TOPGEN]) == tg, bar);
;             __builtin_amdgcn_fence(__ATOMIC_ACQUIRE, "agent");
;             xb_add(&bar[XB_XGEN(bx)], 1u);
;             asm volatile("s_waitcnt vmcnt(0)" ::: "memory");
;         } else {
;             XB_SPIN(xb_ld(&bar[XB_XGEN(bx)]) == gen, bar);
;             __builtin_amdgcn_fence(__ATOMIC_ACQUIRE, "agent");
;             asm volatile("s_waitcnt vmcnt(0)" ::: "memory");
;         }
;     }
;     __syncthreads();
.LBB0_606:
	s_waitcnt vmcnt(0)
	s_waitcnt lgkmcnt(0)
	s_barrier
	s_mov_b64 s[42:43], exec
	v_readlane_b32 s2, v253, 5
	v_readlane_b32 s3, v253, 6
	s_and_b64 s[2:3], s[42:43], s[2:3]
	s_mov_b64 exec, s[2:3]
	s_cbranch_execz .LBB0_650
	v_mov_b32_e32 v0, 0x20fa0
	ds_read_b64 v[2:3], v0
	v_readlane_b32 s10, v253, 2
	v_readlane_b32 s11, v253, 3
	s_add_u32 s10, s10, 0x3b00
	s_addc_u32 s11, s11, 0
	v_mov_b64_e32 v[4:5], s[10:11]
	s_waitcnt lgkmcnt(0)
	v_readfirstlane_b32 s14, v3
	s_mul_i32 s14, s14, s98
	s_mov_b32 s16, 0
